# K-loop: m0 write moved ahead of the address VALU so the VALU supplies the m0 wait state, 11 s_nop pads removed
# baseline (speedup 1.0000x reference)
; #define PG8_STAGE(bufoff, gbase, voff) do { _Pragma("unroll") for (int _i = 0; _i < 2; ++_i) \
;         __builtin_amdgcn_global_load_lds((const unsigned*)((const char*)(gbase) + (voff)[_i]), (LAS unsigned*)(lds + (bufoff) + ldsw + _i * 8192), 16, 0, 0); } while (0)
; #define PG8_LDA(dst, b, h) do { _Pragma("unroll") for (int m = 0; m < 4; ++m) _Pragma("unroll") for (int k = 0; k < 2; ++k) dst[m][k] = *(const LAS bf16x8*)(lds + PG8_SA(b, h) + aoff + m * 2048 + k * 1024); } while (0)
; #define PG8_LDB(dst, b, h) do { _Pragma("unroll") for (int n = 0; n < 2; ++n) _Pragma("unroll") for (int k = 0; k < 2; ++k) dst[n][k] = *(const LAS bf16x8*)(lds + PG8_SB(b, h) + boff + n * 2048 + k * 1024); } while (0)
; #define PG8_MMA(ai, bj, At, Bt) do { __builtin_amdgcn_s_setprio(1); _Pragma("unroll") for (int m = 0; m < 4; ++m) _Pragma("unroll") for (int n = 0; n < 2; ++n) _Pragma("unroll") for (int k = 0; k < 2; ++k) \
;         acc[ai][bj][m][n] = __builtin_amdgcn_mfma_f32_16x16x32_bf16(Bt[n][k], At[m][k], acc[ai][bj][m][n], 0, 0, 0); __builtin_amdgcn_s_setprio(0); } while (0)
; #define PG8_WAIT_V(n) asm volatile("s_waitcnt vmcnt(" #n ")" ::: "memory")
; #define PG8_WAIT_L(n) asm volatile("s_waitcnt lgkmcnt(" #n ")" ::: "memory")
; #define PG8_BAR __builtin_amdgcn_s_barrier()
; #define PG8_SCHED __builtin_amdgcn_sched_barrier(0)
; __device__ __forceinline__ void gemm_phase(const int bid, const int nblk, LAS unsigned char* lds, const int garg, const int chunk, const Params& p) {
;     ...
;             PG8_LDB(B0, 0, 0); PG8_SCHED; PG8_LDA(At, 0, 0); PG8_STAGE(PG8_SA(1, 1), a1 + hstepA, voffA);
;             PG8_WAIT_L(8); PG8_BAR; PG8_WAIT_L(0); PG8_MMA(0, 0, At, B0); PG8_BAR; PG8_SCHED;
;             PG8_LDB(B1, 0, 1); PG8_STAGE(PG8_SB(0, 0), b2, voffB);
;             PG8_BAR; PG8_WAIT_L(0); PG8_MMA(0, 1, At, B1); PG8_BAR;
;             PG8_LDA(At, 0, 1); PG8_STAGE(PG8_SA(0, 0), a2, voffA);
;             PG8_BAR; PG8_WAIT_L(0); PG8_MMA(1, 0, At, B0); PG8_BAR; PG8_SCHED;
;             PG8_STAGE(PG8_SB(0, 1), b2 + hstepB, voffB);
;             PG8_WAIT_V(6); PG8_BAR; PG8_MMA(1, 1, At, B1); PG8_BAR;
.Lprio_skip:
	s_waitcnt vmcnt(0)
	s_add_i32 s30, s8, 2
	s_add_u32 s12, s2, 0x80
	s_addc_u32 s9, s3, 0
	s_add_i32 s31, 0, 0x10000
	v_add_u32_e32 v10, s31, v234
	ds_read_b128 v[134:137], v10
	ds_read_b128 v[138:141], v10 offset:1024
	ds_read_b128 v[142:145], v10 offset:2048
	ds_read_b128 v[146:149], v10 offset:3072
	s_cmp_eq_u32 s27, s8
	s_cselect_b32 s8, s74, s12
	s_cselect_b32 s9, s75, s9
	s_cselect_b32 s13, s79, s15
	s_cselect_b32 s12, s78, s14
	v_lshl_add_u64 v[12:13], s[2:3], 0, v[176:177]
	s_add_i32 m0, s65, 0xc000
	ds_read_b128 v[150:153], v240
	ds_read_b128 v[154:157], v240 offset:1024
	ds_read_b128 v[182:185], v240 offset:2048
	ds_read_b128 v[186:189], v240 offset:3072
	ds_read_b128 v[190:193], v240 offset:4096
	ds_read_b128 v[194:197], v240 offset:5120
	ds_read_b128 v[198:201], v240 offset:6144
	ds_read_b128 v[202:205], v240 offset:7168
	global_load_lds_dwordx4 v[12:13], off
	s_add_i32 m0, s65, 0xe000
	v_lshl_add_u64 v[12:13], s[2:3], 0, v[178:179]
	global_load_lds_dwordx4 v[12:13], off
	s_waitcnt lgkmcnt(8)
	s_barrier
	s_waitcnt lgkmcnt(0)
	v_mfma_f32_16x16x32_bf16 v[130:133], v[134:137], v[150:153], 0
	v_mfma_f32_16x16x32_bf16 v[126:129], v[142:145], v[150:153], 0
	v_mfma_f32_16x16x32_bf16 v[114:117], v[134:137], v[182:185], 0
	v_mfma_f32_16x16x32_bf16 v[110:113], v[142:145], v[182:185], 0
	v_mfma_f32_16x16x32_bf16 v[98:101], v[134:137], v[190:193], 0
	v_mfma_f32_16x16x32_bf16 v[94:97], v[142:145], v[190:193], 0
	v_mfma_f32_16x16x32_bf16 v[82:85], v[134:137], v[198:201], 0
	v_mfma_f32_16x16x32_bf16 v[78:81], v[142:145], v[198:201], 0
	v_mfma_f32_16x16x32_bf16 v[130:133], v[138:141], v[154:157], v[130:133]
	v_mfma_f32_16x16x32_bf16 v[126:129], v[146:149], v[154:157], v[126:129]
	v_mfma_f32_16x16x32_bf16 v[114:117], v[138:141], v[186:189], v[114:117]
	v_mfma_f32_16x16x32_bf16 v[110:113], v[146:149], v[186:189], v[110:113]
	v_mfma_f32_16x16x32_bf16 v[98:101], v[138:141], v[194:197], v[98:101]
	v_mfma_f32_16x16x32_bf16 v[94:97], v[146:149], v[194:197], v[94:97]
	v_mfma_f32_16x16x32_bf16 v[82:85], v[138:141], v[202:205], v[82:85]
	v_mfma_f32_16x16x32_bf16 v[78:81], v[146:149], v[202:205], v[78:81]
	s_barrier
	s_add_i32 s36, 0, 0x14000
	s_add_i32 s31, s31, s64
	v_add_u32_e32 v10, s36, v234
	v_lshl_add_u64 v[210:211], s[12:13], 0, v[164:165]
	s_mov_b32 m0, s31
	ds_read_b128 v[206:209], v10
	ds_read_b128 v[242:245], v10 offset:1024
	ds_read_b128 v[246:249], v10 offset:2048
	ds_read_b128 v[250:253], v10 offset:3072
	global_load_lds_dwordx4 v[210:211], off
	s_add_i32 m0, s31, 0x2000
	v_lshl_add_u64 v[216:217], s[12:13], 0, v[160:161]
	global_load_lds_dwordx4 v[216:217], off
	s_barrier
	s_waitcnt lgkmcnt(0)
	v_mfma_f32_16x16x32_bf16 v[122:125], v[206:209], v[150:153], 0
	v_mfma_f32_16x16x32_bf16 v[118:121], v[246:249], v[150:153], 0
	v_mfma_f32_16x16x32_bf16 v[106:109], v[206:209], v[182:185], 0
	v_mfma_f32_16x16x32_bf16 v[102:105], v[246:249], v[182:185], 0
	v_mfma_f32_16x16x32_bf16 v[90:93], v[206:209], v[190:193], 0
	v_mfma_f32_16x16x32_bf16 v[86:89], v[246:249], v[190:193], 0
	v_mfma_f32_16x16x32_bf16 v[74:77], v[206:209], v[198:201], 0
	v_mfma_f32_16x16x32_bf16 v[70:73], v[246:249], v[198:201], 0
	v_mfma_f32_16x16x32_bf16 v[122:125], v[242:245], v[154:157], v[122:125]
	v_mfma_f32_16x16x32_bf16 v[118:121], v[250:253], v[154:157], v[118:121]
	v_mfma_f32_16x16x32_bf16 v[106:109], v[242:245], v[186:189], v[106:109]
	v_mfma_f32_16x16x32_bf16 v[102:105], v[250:253], v[186:189], v[102:105]
	v_mfma_f32_16x16x32_bf16 v[90:93], v[242:245], v[194:197], v[90:93]
	v_mfma_f32_16x16x32_bf16 v[86:89], v[250:253], v[194:197], v[86:89]
	v_mfma_f32_16x16x32_bf16 v[74:77], v[242:245], v[202:205], v[74:77]
	v_mfma_f32_16x16x32_bf16 v[70:73], v[250:253], v[202:205], v[70:73]
	s_mov_b32 m0, s65
	v_lshl_add_u64 v[222:223], s[8:9], 0, v[162:163]
	s_barrier
	ds_read_b128 v[150:153], v240 offset:16384
	ds_read_b128 v[154:157], v240 offset:17408
	ds_read_b128 v[182:185], v240 offset:18432
	ds_read_b128 v[186:189], v240 offset:19456
	ds_read_b128 v[190:193], v240 offset:20480
	ds_read_b128 v[194:197], v240 offset:21504
	ds_read_b128 v[198:201], v240 offset:22528
	ds_read_b128 v[202:205], v240 offset:23552
	global_load_lds_dwordx4 v[222:223], off
	s_mov_b32 m0, s71
	v_lshl_add_u64 v[224:225], s[8:9], 0, v[8:9]
	global_load_lds_dwordx4 v[224:225], off
	s_barrier
	s_waitcnt lgkmcnt(0)
	v_mfma_f32_16x16x32_bf16 v[66:69], v[134:137], v[150:153], 0
	v_mfma_f32_16x16x32_bf16 v[62:65], v[142:145], v[150:153], 0
	v_mfma_f32_16x16x32_bf16 v[50:53], v[134:137], v[182:185], 0
	v_mfma_f32_16x16x32_bf16 v[46:49], v[142:145], v[182:185], 0
	v_mfma_f32_16x16x32_bf16 v[34:37], v[134:137], v[190:193], 0
	v_mfma_f32_16x16x32_bf16 v[30:33], v[142:145], v[190:193], 0
	v_mfma_f32_16x16x32_bf16 v[18:21], v[134:137], v[198:201], 0
	v_mfma_f32_16x16x32_bf16 v[12:15], v[142:145], v[198:201], 0
	v_mfma_f32_16x16x32_bf16 v[66:69], v[138:141], v[154:157], v[66:69]
	v_mfma_f32_16x16x32_bf16 v[62:65], v[146:149], v[154:157], v[62:65]
	v_mfma_f32_16x16x32_bf16 v[50:53], v[138:141], v[186:189], v[50:53]
	v_mfma_f32_16x16x32_bf16 v[46:49], v[146:149], v[186:189], v[46:49]
	v_mfma_f32_16x16x32_bf16 v[34:37], v[138:141], v[194:197], v[34:37]
	v_mfma_f32_16x16x32_bf16 v[30:33], v[146:149], v[194:197], v[30:33]
	v_mfma_f32_16x16x32_bf16 v[18:21], v[138:141], v[202:205], v[18:21]
	v_mfma_f32_16x16x32_bf16 v[12:15], v[146:149], v[202:205], v[12:15]
	s_barrier
	s_add_u32 s12, s12, s66
	s_addc_u32 s13, s13, s67
	s_add_i32 s31, s36, s64
	v_lshl_add_u64 v[220:221], s[12:13], 0, v[164:165]
	s_mov_b32 m0, s31
	v_lshl_add_u64 v[226:227], s[12:13], 0, v[160:161]
	global_load_lds_dwordx4 v[220:221], off
	s_add_i32 m0, s31, 0x2000
	s_nop 0
	global_load_lds_dwordx4 v[226:227], off
	s_waitcnt vmcnt(6)
	s_barrier
	v_mfma_f32_16x16x32_bf16 v[58:61], v[206:209], v[150:153], 0
	v_mfma_f32_16x16x32_bf16 v[54:57], v[246:249], v[150:153], 0
	v_mfma_f32_16x16x32_bf16 v[42:45], v[206:209], v[182:185], 0
	v_mfma_f32_16x16x32_bf16 v[38:41], v[246:249], v[182:185], 0
	v_mfma_f32_16x16x32_bf16 v[26:29], v[206:209], v[190:193], 0
	v_mfma_f32_16x16x32_bf16 v[22:25], v[246:249], v[190:193], 0
	v_mfma_f32_16x16x32_bf16 v[4:7], v[206:209], v[198:201], 0
	v_mfma_f32_16x16x32_bf16 v[0:3], v[246:249], v[198:201], 0
	v_mfma_f32_16x16x32_bf16 v[58:61], v[242:245], v[154:157], v[58:61]
	v_mfma_f32_16x16x32_bf16 v[54:57], v[250:253], v[154:157], v[54:57]
	v_mfma_f32_16x16x32_bf16 v[42:45], v[242:245], v[186:189], v[42:45]
	v_mfma_f32_16x16x32_bf16 v[38:41], v[250:253], v[186:189], v[38:41]
	v_mfma_f32_16x16x32_bf16 v[26:29], v[242:245], v[194:197], v[26:29]
	v_mfma_f32_16x16x32_bf16 v[22:25], v[250:253], v[194:197], v[22:25]
	v_mfma_f32_16x16x32_bf16 v[4:7], v[242:245], v[202:205], v[4:7]
	v_mfma_f32_16x16x32_bf16 v[0:3], v[250:253], v[202:205], v[0:3]
	s_branch .Lk_mid
; #define PG8_STAGE(bufoff, gbase, voff) do { _Pragma("unroll") for (int _i = 0; _i < 2; ++_i) \
;         __builtin_amdgcn_global_load_lds((const unsigned*)((const char*)(gbase) + (voff)[_i]), (LAS unsigned*)(lds + (bufoff) + ldsw + _i * 8192), 16, 0, 0); } while (0)
; #define PG8_LDA(dst, b, h) do { _Pragma("unroll") for (int m = 0; m < 4; ++m) _Pragma("unroll") for (int k = 0; k < 2; ++k) dst[m][k] = *(const LAS bf16x8*)(lds + PG8_SA(b, h) + aoff + m * 2048 + k * 1024); } while (0)
; #define PG8_LDB(dst, b, h) do { _Pragma("unroll") for (int n = 0; n < 2; ++n) _Pragma("unroll") for (int k = 0; k < 2; ++k) dst[n][k] = *(const LAS bf16x8*)(lds + PG8_SB(b, h) + boff + n * 2048 + k * 1024); } while (0)
; #define PG8_MMA(ai, bj, At, Bt) do { __builtin_amdgcn_s_setprio(1); _Pragma("unroll") for (int m = 0; m < 4; ++m) _Pragma("unroll") for (int n = 0; n < 2; ++n) _Pragma("unroll") for (int k = 0; k < 2; ++k) \
;         acc[ai][bj][m][n] = __builtin_amdgcn_mfma_f32_16x16x32_bf16(Bt[n][k], At[m][k], acc[ai][bj][m][n], 0, 0, 0); __builtin_amdgcn_s_setprio(0); } while (0)
; #define PG8_WAIT_V(n) asm volatile("s_waitcnt vmcnt(" #n ")" ::: "memory")
; #define PG8_WAIT_L(n) asm volatile("s_waitcnt lgkmcnt(" #n ")" ::: "memory")
; #define PG8_BAR __builtin_amdgcn_s_barrier()
; #define PG8_SCHED __builtin_amdgcn_sched_barrier(0)
; __device__ __forceinline__ void gemm_phase(const int bid, const int nblk, LAS unsigned char* lds, const int garg, const int chunk, const Params& p) {
;     ...
;             PG8_LDB(B0, 0, 0); PG8_SCHED; PG8_LDA(At, 0, 0); PG8_STAGE(PG8_SA(1, 1), a1 + hstepA, voffA);
;             PG8_WAIT_L(8); PG8_BAR; PG8_WAIT_L(0); PG8_MMA(0, 0, At, B0); PG8_BAR; PG8_SCHED;
;             PG8_LDB(B1, 0, 1); PG8_STAGE(PG8_SB(0, 0), b2, voffB);
;             PG8_BAR; PG8_WAIT_L(0); PG8_MMA(0, 1, At, B1); PG8_BAR;
;             PG8_LDA(At, 0, 1); PG8_STAGE(PG8_SA(0, 0), a2, voffA);
;             PG8_BAR; PG8_WAIT_L(0); PG8_MMA(1, 0, At, B0); PG8_BAR; PG8_SCHED;
;             PG8_STAGE(PG8_SB(0, 1), b2 + hstepB, voffB);
;             PG8_WAIT_V(6); PG8_BAR; PG8_MMA(1, 1, At, B1); PG8_BAR;
.LBB0_441:
	s_add_i32 s30, s8, 2
	s_add_u32 s12, s2, 0x80
	s_addc_u32 s9, s3, 0
	s_add_i32 s31, 0, 0x10000
	v_add_u32_e32 v10, s31, v234
	ds_read_b128 v[134:137], v10
	ds_read_b128 v[138:141], v10 offset:1024
	ds_read_b128 v[142:145], v10 offset:2048
	ds_read_b128 v[146:149], v10 offset:3072
	s_cmp_eq_u32 s27, s8
	s_cselect_b32 s8, s74, s12
	s_cselect_b32 s9, s75, s9
	s_cselect_b32 s13, s79, s15
	s_cselect_b32 s12, s78, s14
	v_lshl_add_u64 v[12:13], s[2:3], 0, v[176:177]
	s_add_i32 m0, s65, 0xc000
	ds_read_b128 v[150:153], v240
	ds_read_b128 v[154:157], v240 offset:1024
	ds_read_b128 v[182:185], v240 offset:2048
	ds_read_b128 v[186:189], v240 offset:3072
	ds_read_b128 v[190:193], v240 offset:4096
	ds_read_b128 v[194:197], v240 offset:5120
	ds_read_b128 v[198:201], v240 offset:6144
	ds_read_b128 v[202:205], v240 offset:7168
	global_load_lds_dwordx4 v[12:13], off
	s_add_i32 m0, s65, 0xe000
	v_lshl_add_u64 v[12:13], s[2:3], 0, v[178:179]
	global_load_lds_dwordx4 v[12:13], off
	s_waitcnt lgkmcnt(8)
	s_barrier
	s_waitcnt lgkmcnt(0)
	v_mfma_f32_16x16x32_bf16 v[130:133], v[134:137], v[150:153], v[130:133]
	v_mfma_f32_16x16x32_bf16 v[126:129], v[142:145], v[150:153], v[126:129]
	v_mfma_f32_16x16x32_bf16 v[114:117], v[134:137], v[182:185], v[114:117]
	v_mfma_f32_16x16x32_bf16 v[110:113], v[142:145], v[182:185], v[110:113]
	v_mfma_f32_16x16x32_bf16 v[98:101], v[134:137], v[190:193], v[98:101]
	v_mfma_f32_16x16x32_bf16 v[94:97], v[142:145], v[190:193], v[94:97]
	v_mfma_f32_16x16x32_bf16 v[82:85], v[134:137], v[198:201], v[82:85]
	v_mfma_f32_16x16x32_bf16 v[78:81], v[142:145], v[198:201], v[78:81]
	v_mfma_f32_16x16x32_bf16 v[130:133], v[138:141], v[154:157], v[130:133]
	v_mfma_f32_16x16x32_bf16 v[126:129], v[146:149], v[154:157], v[126:129]
	v_mfma_f32_16x16x32_bf16 v[114:117], v[138:141], v[186:189], v[114:117]
	v_mfma_f32_16x16x32_bf16 v[110:113], v[146:149], v[186:189], v[110:113]
	v_mfma_f32_16x16x32_bf16 v[98:101], v[138:141], v[194:197], v[98:101]
	v_mfma_f32_16x16x32_bf16 v[94:97], v[146:149], v[194:197], v[94:97]
	v_mfma_f32_16x16x32_bf16 v[82:85], v[138:141], v[202:205], v[82:85]
	v_mfma_f32_16x16x32_bf16 v[78:81], v[146:149], v[202:205], v[78:81]
	s_barrier
	s_add_i32 s36, 0, 0x14000
	s_add_i32 s31, s31, s64
	v_add_u32_e32 v10, s36, v234
	v_lshl_add_u64 v[210:211], s[12:13], 0, v[164:165]
	s_mov_b32 m0, s31
	ds_read_b128 v[206:209], v10
	ds_read_b128 v[242:245], v10 offset:1024
	ds_read_b128 v[246:249], v10 offset:2048
	ds_read_b128 v[250:253], v10 offset:3072
	global_load_lds_dwordx4 v[210:211], off
	s_add_i32 m0, s31, 0x2000
	v_lshl_add_u64 v[216:217], s[12:13], 0, v[160:161]
	global_load_lds_dwordx4 v[216:217], off
	s_barrier
	s_waitcnt lgkmcnt(0)
	v_mfma_f32_16x16x32_bf16 v[122:125], v[206:209], v[150:153], v[122:125]
	v_mfma_f32_16x16x32_bf16 v[118:121], v[246:249], v[150:153], v[118:121]
	v_mfma_f32_16x16x32_bf16 v[106:109], v[206:209], v[182:185], v[106:109]
	v_mfma_f32_16x16x32_bf16 v[102:105], v[246:249], v[182:185], v[102:105]
	v_mfma_f32_16x16x32_bf16 v[90:93], v[206:209], v[190:193], v[90:93]
	v_mfma_f32_16x16x32_bf16 v[86:89], v[246:249], v[190:193], v[86:89]
	v_mfma_f32_16x16x32_bf16 v[74:77], v[206:209], v[198:201], v[74:77]
	v_mfma_f32_16x16x32_bf16 v[70:73], v[246:249], v[198:201], v[70:73]
	v_mfma_f32_16x16x32_bf16 v[122:125], v[242:245], v[154:157], v[122:125]
	v_mfma_f32_16x16x32_bf16 v[118:121], v[250:253], v[154:157], v[118:121]
	v_mfma_f32_16x16x32_bf16 v[106:109], v[242:245], v[186:189], v[106:109]
	v_mfma_f32_16x16x32_bf16 v[102:105], v[250:253], v[186:189], v[102:105]
	v_mfma_f32_16x16x32_bf16 v[90:93], v[242:245], v[194:197], v[90:93]
	v_mfma_f32_16x16x32_bf16 v[86:89], v[250:253], v[194:197], v[86:89]
	v_mfma_f32_16x16x32_bf16 v[74:77], v[242:245], v[202:205], v[74:77]
	v_mfma_f32_16x16x32_bf16 v[70:73], v[250:253], v[202:205], v[70:73]
	s_mov_b32 m0, s65
	v_lshl_add_u64 v[222:223], s[8:9], 0, v[162:163]
	s_barrier
	ds_read_b128 v[150:153], v240 offset:16384
	ds_read_b128 v[154:157], v240 offset:17408
	ds_read_b128 v[182:185], v240 offset:18432
	ds_read_b128 v[186:189], v240 offset:19456
	ds_read_b128 v[190:193], v240 offset:20480
	ds_read_b128 v[194:197], v240 offset:21504
	ds_read_b128 v[198:201], v240 offset:22528
	ds_read_b128 v[202:205], v240 offset:23552
	global_load_lds_dwordx4 v[222:223], off
	s_mov_b32 m0, s71
	v_lshl_add_u64 v[224:225], s[8:9], 0, v[8:9]
	global_load_lds_dwordx4 v[224:225], off
	s_barrier
	s_waitcnt lgkmcnt(0)
	v_mfma_f32_16x16x32_bf16 v[66:69], v[134:137], v[150:153], v[66:69]
	v_mfma_f32_16x16x32_bf16 v[62:65], v[142:145], v[150:153], v[62:65]
	v_mfma_f32_16x16x32_bf16 v[50:53], v[134:137], v[182:185], v[50:53]
	v_mfma_f32_16x16x32_bf16 v[46:49], v[142:145], v[182:185], v[46:49]
	v_mfma_f32_16x16x32_bf16 v[34:37], v[134:137], v[190:193], v[34:37]
	v_mfma_f32_16x16x32_bf16 v[30:33], v[142:145], v[190:193], v[30:33]
	v_mfma_f32_16x16x32_bf16 v[18:21], v[134:137], v[198:201], v[18:21]
	v_mfma_f32_16x16x32_bf16 v[12:15], v[142:145], v[198:201], v[14:17]
	v_mfma_f32_16x16x32_bf16 v[66:69], v[138:141], v[154:157], v[66:69]
	v_mfma_f32_16x16x32_bf16 v[62:65], v[146:149], v[154:157], v[62:65]
	v_mfma_f32_16x16x32_bf16 v[50:53], v[138:141], v[186:189], v[50:53]
	v_mfma_f32_16x16x32_bf16 v[46:49], v[146:149], v[186:189], v[46:49]
	v_mfma_f32_16x16x32_bf16 v[34:37], v[138:141], v[194:197], v[34:37]
	v_mfma_f32_16x16x32_bf16 v[30:33], v[146:149], v[194:197], v[30:33]
	v_mfma_f32_16x16x32_bf16 v[18:21], v[138:141], v[202:205], v[18:21]
	v_mfma_f32_16x16x32_bf16 v[12:15], v[146:149], v[202:205], v[12:15]
	s_barrier
	s_add_u32 s12, s12, s66
	s_addc_u32 s13, s13, s67
	s_add_i32 s31, s36, s64
	v_lshl_add_u64 v[220:221], s[12:13], 0, v[164:165]
	s_mov_b32 m0, s31
	v_lshl_add_u64 v[226:227], s[12:13], 0, v[160:161]
	global_load_lds_dwordx4 v[220:221], off
	s_add_i32 m0, s31, 0x2000
	s_nop 0
	global_load_lds_dwordx4 v[226:227], off
	s_waitcnt vmcnt(6)
	s_barrier
	v_mfma_f32_16x16x32_bf16 v[58:61], v[206:209], v[150:153], v[58:61]
	v_mfma_f32_16x16x32_bf16 v[54:57], v[246:249], v[150:153], v[54:57]
	v_mfma_f32_16x16x32_bf16 v[42:45], v[206:209], v[182:185], v[42:45]
	v_mfma_f32_16x16x32_bf16 v[38:41], v[246:249], v[182:185], v[38:41]
	v_mfma_f32_16x16x32_bf16 v[26:29], v[206:209], v[190:193], v[26:29]
	v_mfma_f32_16x16x32_bf16 v[22:25], v[246:249], v[190:193], v[22:25]
	v_mfma_f32_16x16x32_bf16 v[4:7], v[206:209], v[198:201], v[4:7]
	v_mfma_f32_16x16x32_bf16 v[0:3], v[246:249], v[198:201], v[0:3]
	v_mfma_f32_16x16x32_bf16 v[58:61], v[242:245], v[154:157], v[58:61]
	v_mfma_f32_16x16x32_bf16 v[54:57], v[250:253], v[154:157], v[54:57]
	v_mfma_f32_16x16x32_bf16 v[42:45], v[242:245], v[186:189], v[42:45]
	v_mfma_f32_16x16x32_bf16 v[38:41], v[250:253], v[186:189], v[38:41]
	v_mfma_f32_16x16x32_bf16 v[26:29], v[242:245], v[194:197], v[26:29]
	v_mfma_f32_16x16x32_bf16 v[22:25], v[250:253], v[194:197], v[22:25]
	v_mfma_f32_16x16x32_bf16 v[4:7], v[242:245], v[202:205], v[4:7]
	v_mfma_f32_16x16x32_bf16 v[0:3], v[250:253], v[202:205], v[0:3]
; #define PG8_STAGE(bufoff, gbase, voff) do { _Pragma("unroll") for (int _i = 0; _i < 2; ++_i) \
;         __builtin_amdgcn_global_load_lds((const unsigned*)((const char*)(gbase) + (voff)[_i]), (LAS unsigned*)(lds + (bufoff) + ldsw + _i * 8192), 16, 0, 0); } while (0)
; #define PG8_LDA(dst, b, h) do { _Pragma("unroll") for (int m = 0; m < 4; ++m) _Pragma("unroll") for (int k = 0; k < 2; ++k) dst[m][k] = *(const LAS bf16x8*)(lds + PG8_SA(b, h) + aoff + m * 2048 + k * 1024); } while (0)
; #define PG8_LDB(dst, b, h) do { _Pragma("unroll") for (int n = 0; n < 2; ++n) _Pragma("unroll") for (int k = 0; k < 2; ++k) dst[n][k] = *(const LAS bf16x8*)(lds + PG8_SB(b, h) + boff + n * 2048 + k * 1024); } while (0)
; #define PG8_MMA(ai, bj, At, Bt) do { __builtin_amdgcn_s_setprio(1); _Pragma("unroll") for (int m = 0; m < 4; ++m) _Pragma("unroll") for (int n = 0; n < 2; ++n) _Pragma("unroll") for (int k = 0; k < 2; ++k) \
;         acc[ai][bj][m][n] = __builtin_amdgcn_mfma_f32_16x16x32_bf16(Bt[n][k], At[m][k], acc[ai][bj][m][n], 0, 0, 0); __builtin_amdgcn_s_setprio(0); } while (0)
; #define PG8_WAIT_V(n) asm volatile("s_waitcnt vmcnt(" #n ")" ::: "memory")
; #define PG8_WAIT_L(n) asm volatile("s_waitcnt lgkmcnt(" #n ")" ::: "memory")
; #define PG8_BAR __builtin_amdgcn_s_barrier()
; #define PG8_SCHED __builtin_amdgcn_sched_barrier(0)
; __device__ __forceinline__ void gemm_phase(const int bid, const int nblk, LAS unsigned char* lds, const int garg, const int chunk, const Params& p) {
;     ...
;             PG8_LDB(B0, 1, 0); PG8_SCHED; PG8_LDA(At, 1, 0); PG8_STAGE(PG8_SA(0, 1), a2 + hstepA, voffA);
;             PG8_WAIT_L(8); PG8_BAR; PG8_WAIT_L(0); PG8_MMA(0, 0, At, B0); PG8_BAR; PG8_SCHED;
;             PG8_LDB(B1, 1, 1); PG8_STAGE(PG8_SB(1, 0), b3, voffB);
;             PG8_BAR; PG8_WAIT_L(0); PG8_MMA(0, 1, At, B1); PG8_BAR;
;             PG8_LDA(At, 1, 1); PG8_STAGE(PG8_SA(1, 0), a3, voffA);
;             PG8_BAR; PG8_WAIT_L(0); PG8_MMA(1, 0, At, B0); PG8_BAR; PG8_SCHED;
;             PG8_STAGE(PG8_SB(1, 1), b3 + hstepB, voffB);
;             PG8_WAIT_V(6); PG8_BAR; PG8_MMA(1, 1, At, B1); PG8_BAR;
.Lk_mid:
	s_add_i32 s12, 0, 0x18000
	v_add_u32_e32 v10, s12, v234
	s_barrier
	ds_read_b128 v[134:137], v10
	ds_read_b128 v[138:141], v10 offset:1024
	ds_read_b128 v[142:145], v10 offset:2048
	ds_read_b128 v[146:149], v10 offset:3072
	s_add_u32 s8, s8, s88
	s_addc_u32 s9, s9, s89
	s_mov_b32 m0, s63
	v_lshl_add_u64 v[16:17], s[8:9], 0, v[162:163]
	ds_read_b128 v[150:153], v240 offset:32768
	ds_read_b128 v[154:157], v240 offset:33792
	ds_read_b128 v[182:185], v240 offset:34816
	ds_read_b128 v[186:189], v240 offset:35840
	ds_read_b128 v[190:193], v240 offset:36864
	ds_read_b128 v[194:197], v240 offset:37888
	ds_read_b128 v[198:201], v240 offset:38912
	ds_read_b128 v[202:205], v240 offset:39936
	global_load_lds_dwordx4 v[16:17], off
	s_mov_b32 m0, s19
	v_lshl_add_u64 v[16:17], s[8:9], 0, v[8:9]
	global_load_lds_dwordx4 v[16:17], off
	s_waitcnt lgkmcnt(8)
	s_barrier
	s_waitcnt lgkmcnt(0)
	v_mfma_f32_16x16x32_bf16 v[130:133], v[134:137], v[150:153], v[130:133]
	v_mfma_f32_16x16x32_bf16 v[126:129], v[142:145], v[150:153], v[126:129]
	v_mfma_f32_16x16x32_bf16 v[114:117], v[134:137], v[182:185], v[114:117]
	v_mfma_f32_16x16x32_bf16 v[110:113], v[142:145], v[182:185], v[110:113]
	v_mfma_f32_16x16x32_bf16 v[98:101], v[134:137], v[190:193], v[98:101]
	v_mfma_f32_16x16x32_bf16 v[94:97], v[142:145], v[190:193], v[94:97]
	v_mfma_f32_16x16x32_bf16 v[82:85], v[134:137], v[198:201], v[82:85]
	v_mfma_f32_16x16x32_bf16 v[78:81], v[142:145], v[198:201], v[78:81]
	v_mfma_f32_16x16x32_bf16 v[130:133], v[138:141], v[154:157], v[130:133]
	v_mfma_f32_16x16x32_bf16 v[126:129], v[146:149], v[154:157], v[126:129]
	v_mfma_f32_16x16x32_bf16 v[114:117], v[138:141], v[186:189], v[114:117]
	v_mfma_f32_16x16x32_bf16 v[110:113], v[146:149], v[186:189], v[110:113]
	v_mfma_f32_16x16x32_bf16 v[98:101], v[138:141], v[194:197], v[98:101]
	v_mfma_f32_16x16x32_bf16 v[94:97], v[146:149], v[194:197], v[94:97]
	v_mfma_f32_16x16x32_bf16 v[82:85], v[138:141], v[202:205], v[82:85]
	v_mfma_f32_16x16x32_bf16 v[78:81], v[146:149], v[202:205], v[78:81]
	s_barrier
	s_add_i32 s8, 0, 0x1c000
	s_add_i32 s9, s12, s64
	v_add_u32_e32 v10, s8, v234
	v_lshl_add_u64 v[16:17], v[210:211], 0, s[92:93]
	s_mov_b32 m0, s9
	ds_read_b128 v[206:209], v10
	ds_read_b128 v[242:245], v10 offset:1024
	ds_read_b128 v[246:249], v10 offset:2048
	ds_read_b128 v[250:253], v10 offset:3072
	global_load_lds_dwordx4 v[16:17], off
	s_add_i32 m0, s9, 0x2000
	v_lshl_add_u64 v[16:17], v[216:217], 0, s[92:93]
	global_load_lds_dwordx4 v[16:17], off
	s_barrier
	s_waitcnt lgkmcnt(0)
	v_mfma_f32_16x16x32_bf16 v[122:125], v[206:209], v[150:153], v[122:125]
	v_mfma_f32_16x16x32_bf16 v[118:121], v[246:249], v[150:153], v[118:121]
	v_mfma_f32_16x16x32_bf16 v[106:109], v[206:209], v[182:185], v[106:109]
	v_mfma_f32_16x16x32_bf16 v[102:105], v[246:249], v[182:185], v[102:105]
	v_mfma_f32_16x16x32_bf16 v[90:93], v[206:209], v[190:193], v[90:93]
	v_mfma_f32_16x16x32_bf16 v[86:89], v[246:249], v[190:193], v[86:89]
	v_mfma_f32_16x16x32_bf16 v[74:77], v[206:209], v[198:201], v[74:77]
	v_mfma_f32_16x16x32_bf16 v[70:73], v[246:249], v[198:201], v[70:73]
	v_mfma_f32_16x16x32_bf16 v[122:125], v[242:245], v[154:157], v[122:125]
	v_mfma_f32_16x16x32_bf16 v[118:121], v[250:253], v[154:157], v[118:121]
	v_mfma_f32_16x16x32_bf16 v[106:109], v[242:245], v[186:189], v[106:109]
	v_mfma_f32_16x16x32_bf16 v[102:105], v[250:253], v[186:189], v[102:105]
	v_mfma_f32_16x16x32_bf16 v[90:93], v[242:245], v[194:197], v[90:93]
	v_mfma_f32_16x16x32_bf16 v[86:89], v[250:253], v[194:197], v[86:89]
	v_mfma_f32_16x16x32_bf16 v[74:77], v[242:245], v[202:205], v[74:77]
	v_mfma_f32_16x16x32_bf16 v[70:73], v[250:253], v[202:205], v[70:73]
	s_mov_b32 m0, s70
	v_lshl_add_u64 v[16:17], v[222:223], 0, s[92:93]
	s_barrier
	ds_read_b128 v[150:153], v240 offset:49152
	ds_read_b128 v[154:157], v240 offset:50176
	ds_read_b128 v[182:185], v240 offset:51200
	ds_read_b128 v[186:189], v240 offset:52224
	ds_read_b128 v[190:193], v240 offset:53248
	ds_read_b128 v[194:197], v240 offset:54272
	ds_read_b128 v[198:201], v240 offset:55296
	ds_read_b128 v[202:205], v240 offset:56320
	global_load_lds_dwordx4 v[16:17], off
	s_mov_b32 m0, s54
	v_lshl_add_u64 v[16:17], v[224:225], 0, s[92:93]
	global_load_lds_dwordx4 v[16:17], off
	s_barrier
	s_waitcnt lgkmcnt(0)
	v_mfma_f32_16x16x32_bf16 v[66:69], v[134:137], v[150:153], v[66:69]
	v_mfma_f32_16x16x32_bf16 v[62:65], v[142:145], v[150:153], v[62:65]
	v_mfma_f32_16x16x32_bf16 v[50:53], v[134:137], v[182:185], v[50:53]
	v_mfma_f32_16x16x32_bf16 v[46:49], v[142:145], v[182:185], v[46:49]
	v_mfma_f32_16x16x32_bf16 v[34:37], v[134:137], v[190:193], v[34:37]
	v_mfma_f32_16x16x32_bf16 v[30:33], v[142:145], v[190:193], v[30:33]
	v_mfma_f32_16x16x32_bf16 v[16:19], v[134:137], v[198:201], v[18:21]
	v_mfma_f32_16x16x32_bf16 v[12:15], v[142:145], v[198:201], v[12:15]
	v_mfma_f32_16x16x32_bf16 v[66:69], v[138:141], v[154:157], v[66:69]
	v_mfma_f32_16x16x32_bf16 v[62:65], v[146:149], v[154:157], v[62:65]
	v_mfma_f32_16x16x32_bf16 v[50:53], v[138:141], v[186:189], v[50:53]
	v_mfma_f32_16x16x32_bf16 v[46:49], v[146:149], v[186:189], v[46:49]
	v_mfma_f32_16x16x32_bf16 v[34:37], v[138:141], v[194:197], v[34:37]
	v_mfma_f32_16x16x32_bf16 v[30:33], v[146:149], v[194:197], v[30:33]
	v_mfma_f32_16x16x32_bf16 v[18:21], v[138:141], v[202:205], v[16:19]
	v_mfma_f32_16x16x32_bf16 v[14:17], v[146:149], v[202:205], v[12:15]
	s_barrier
	s_add_i32 s8, s8, s64
	s_mov_b32 m0, s8
	v_lshl_add_u64 v[12:13], v[220:221], 0, s[92:93]
	global_load_lds_dwordx4 v[12:13], off
	s_add_i32 m0, s8, 0x2000
	v_lshl_add_u64 v[12:13], v[226:227], 0, s[92:93]
	global_load_lds_dwordx4 v[12:13], off
	s_waitcnt vmcnt(6)
	s_barrier
	v_mfma_f32_16x16x32_bf16 v[58:61], v[206:209], v[150:153], v[58:61]
	v_mfma_f32_16x16x32_bf16 v[54:57], v[246:249], v[150:153], v[54:57]
	v_mfma_f32_16x16x32_bf16 v[42:45], v[206:209], v[182:185], v[42:45]
	v_mfma_f32_16x16x32_bf16 v[38:41], v[246:249], v[182:185], v[38:41]
	v_mfma_f32_16x16x32_bf16 v[26:29], v[206:209], v[190:193], v[26:29]
	v_mfma_f32_16x16x32_bf16 v[22:25], v[246:249], v[190:193], v[22:25]
	v_mfma_f32_16x16x32_bf16 v[4:7], v[206:209], v[198:201], v[4:7]
	v_mfma_f32_16x16x32_bf16 v[0:3], v[246:249], v[198:201], v[0:3]
	v_mfma_f32_16x16x32_bf16 v[58:61], v[242:245], v[154:157], v[58:61]
	v_mfma_f32_16x16x32_bf16 v[54:57], v[250:253], v[154:157], v[54:57]
	v_mfma_f32_16x16x32_bf16 v[42:45], v[242:245], v[186:189], v[42:45]
	v_mfma_f32_16x16x32_bf16 v[38:41], v[250:253], v[186:189], v[38:41]
	v_mfma_f32_16x16x32_bf16 v[26:29], v[242:245], v[194:197], v[26:29]
	v_mfma_f32_16x16x32_bf16 v[22:25], v[250:253], v[194:197], v[22:25]
	v_mfma_f32_16x16x32_bf16 v[4:7], v[242:245], v[202:205], v[4:7]
	v_mfma_f32_16x16x32_bf16 v[0:3], v[250:253], v[202:205], v[0:3]
	s_add_u32 s2, s2, 0x100
	s_addc_u32 s3, s3, 0
	s_add_u32 s14, s14, 0x100
	s_addc_u32 s15, s15, 0
	s_cmp_ge_i32 s30, s55
	s_mov_b32 s8, s30
	s_barrier
	s_cbranch_scc0 .LBB0_441
	s_branch .LBB0_443
